# phase 0: position-DFT table generated by workgroups 32..159 only (8 iterations each), off the adaLN and sparse-transpose workgroups
# speedup vs baseline: 1.0059x; 1.0059x over previous
; DI unsigned cvtpk(float lo, float hi) { f32x2 v = {lo, hi}; bf16x2_t b = __builtin_convertvector(v, bf16x2_t); return __builtin_bit_cast(unsigned, b); }
; DI void phase0(KP p, char* lds) {
;     ...
;     bf16_t* dl = (bf16_t*)(ws + WS_DLAT);
; #pragma nounroll
;     for (size_t i = gtid; i < (size_t)2048 * 256; i += gstride) {
;       const int sp = (int)(i >> 8), k8 = (int)(i & 255) * 8;
;       float v[8];
; #pragma unroll
;       for (int e = 0; e < 8; ++e) { const int k = k8 + e, s = (k <= 1024) ? k : k - 1024; const int ph = (sp * s) & 2047; const float a = (float)ph * (1.f / 1024.f); v[e] = (k <= 1024) ? cospif(a) : -sinpif(a); }
;       u32x4 o = {cvtpk(v[0], v[1]), cvtpk(v[2], v[3]), cvtpk(v[4], v[5]), cvtpk(v[6], v[7])};
;       *(u32x4*)(dl + (size_t)sp * 2048 + k8) = o;
;     }
.LBB0_401:
	s_mov_b64 s[34:35], 0x3fff
	s_or_b64 exec, exec, s[4:5]
	v_readlane_b32 s50, v254, 29
	v_readlane_b32 s52, v254, 31
	v_readlane_b32 s54, v255, 5
	v_readlane_b32 s56, v255, 14
	v_readlane_b32 s64, v255, 16
	v_readlane_b32 s72, v255, 18
	v_readlane_b32 s2, v254, 47
	v_readlane_b32 s69, v255, 25
	v_readlane_b32 s51, v254, 30
	v_readlane_b32 s53, v254, 32
	v_readlane_b32 s55, v255, 6
	v_readlane_b32 s57, v255, 15
	v_readlane_b32 s65, v255, 17
	v_readlane_b32 s73, v255, 19
	v_cmp_gt_u64_e64 s[42:43], s[24:25], v[4:5]
	v_lshl_add_u32 v8, v2, 3, s2
	s_and_saveexec_b64 s[4:5], s[42:43]
	s_cbranch_execz .LBB0_436
	v_readlane_b32 s18, v253, 15
	s_sub_u32 s18, s18, 0x4000
	s_cmp_lt_u32 s18, 0x10000
	s_cbranch_scc0 .LBB0_436
	s_add_u32 s46, s36, 0x1075100
	v_readlane_b32 s2, v254, 47
	s_addc_u32 s47, s37, 0
	s_mov_b64 s[48:49], 0
	v_lshl_add_u32 v9, v2, 3, s2
	v_subrev_u32_e32 v6, 0x4000, v4
	v_mov_b32_e32 v7, 0
	s_waitcnt vmcnt(0)
	s_branch .LBB0_404
.LBB0_403:
	s_or_b64 exec, exec, s[18:19]
	v_lshrrev_b64 v[18:19], 8, v[6:7]
	v_cvt_pk_bf16_f32 v10, v10, v12
	v_cvt_pk_bf16_f32 v11, v13, v14
	v_cvt_pk_bf16_f32 v12, v15, v16
	v_lshlrev_b64 v[14:15], 12, v[18:19]
	s_mov_b64 s[18:19], 0x10000
	v_lshl_add_u64 v[6:7], v[6:7], 0, s[18:19]
	s_mov_b64 s[18:19], 0x7ffff
	v_lshl_add_u64 v[14:15], s[46:47], 0, v[14:15]
	v_lshlrev_b32_e32 v0, 1, v0
	v_cmp_lt_u64_e64 s[42:43], s[18:19], v[6:7]
	v_readlane_b32 s2, v254, 48
	v_cvt_pk_bf16_f32 v13, v17, v21
	v_lshl_add_u64 v[14:15], v[14:15], 0, v[0:1]
	s_or_b64 s[48:49], s[42:43], s[48:49]
	v_add_u32_e32 v9, s2, v9
	global_store_dwordx4 v[14:15], v[10:13], off
	s_andn2_b64 exec, exec, s[48:49]
	s_cbranch_execz .LBB0_436
